# phase B sweep: ballot masks taken directly from SGPR compare results (24 VALU pairs per tile replaced by s_mov)
# speedup vs baseline: 1.0115x; 1.0027x over previous
; DI void attn_item(const Params& P, unsigned char* smem, bool samp, int b, int c) {
;     ...
;         const bool tail = (kt * 64 + 64 > nkeys);
;         unsigned mv = 0u;
;         for (int hf = 0; hf < 2; ++hf) {
;           const bool valid = !tail || ((kt * 64 + hf * 32 + l32) < nkeys);
;           for (int i = 0; i < 4; ++i) {
;             const unsigned key = mono_key(sc[i][hf]);
;             bool sel = valid && (key >= khi[i]);
;             const bool inb = valid && (key >= klo[i]) && (key < khi[i]);
;             const bool zb = (bst[i] == 255);
;             if (anyzb) {
;               const unsigned long long bal = __ballot(inb && zb);
;               const unsigned mym = g ? (unsigned)(bal >> 32) : (unsigned)bal;
;               const int rank = __popc(mym & ltmask);
;               sel = sel || (inb && zb && (seen[i] + rank < nd[i]));
;               seen[i] += __popc(mym);
;             }
;             const bool cand = inb && !zb;
;             const unsigned long long cb = __ballot(cand);
;             if (cb != 0ull) {
;               const unsigned mym = g ? (unsigned)(cb >> 32) : (unsigned)cb;
;               const int slot = cbase[i] + __popc(mym & ltmask);
;               if (cand && slot < CAND_CAP)
;                 lst[(g + 2 * i) * CAND_CAP + slot] = make_uint2(key, (unsigned)(kt * 64 + hf * 32 + l32));
;               cbase[i] += __popc(mym);
;             }
;             const unsigned long long sb = __ballot(sel);
;             mv = (lane == (2 * i) * 2 + hf) ? (unsigned)sb : mv;
;             mv = (lane == (2 * i + 1) * 2 + hf) ? (unsigned)(sb >> 32) : mv;
;           }
.LBB0_620:
	s_nop 9
	v_med3_f32 v20, v20, 0, v187
	v_mul_f32_e32 v20, v52, v20
	v_med3_f32 v21, v21, 0, v187
	v_fmac_f32_e32 v20, v53, v21
	v_med3_f32 v21, v22, 0, v187
	v_fmac_f32_e32 v20, v54, v21
	v_med3_f32 v21, v23, 0, v187
	v_fmac_f32_e32 v20, v55, v21
	s_cmp_le_u32 s21, s1
	v_add_u32_e32 v21, s21, v195
	s_cselect_b64 s[68:69], -1, 0
	v_cmp_gt_u32_e32 vcc, s0, v21
	s_or_b64 s[66:67], s[68:69], vcc
	v_not_b32_e32 v22, v20
	v_or_b32_e32 v23, 0x80000000, v20
	v_cmp_gt_i32_e32 vcc, 0, v20
	s_nop 1
	v_cndmask_b32_e32 v20, v23, v22, vcc
	v_cmp_ge_u32_e32 vcc, v20, v69
	s_and_b64 s[62:63], s[66:67], vcc
	v_cmp_ge_u32_e32 vcc, v20, v68
	s_and_b64 s[58:59], s[66:67], vcc
	v_cmp_lt_u32_e32 vcc, v20, v69
	v_cndmask_b32_e64 v22, 0, 1, s[88:89]
	s_and_b64 s[64:65], s[58:59], vcc
	v_cmp_ne_u32_e64 s[58:59], 1, v22
	s_andn2_b64 vcc, exec, s[88:89]
	s_cbranch_vccnz .LBB0_622
	s_and_b64 vcc, s[18:19], s[64:65]
	s_mov_b64 s[60:61], vcc
	s_nop 0
	v_cndmask_b32_e64 v126, 0, 1, s[62:63]
	s_nop 0
	v_lshrrev_b64 v[22:23], v114, s[60:61]
	v_and_b32_e32 v23, v22, v109
	v_bcnt_u32_b32 v23, v23, v124
	v_cmp_lt_i32_e64 s[60:61], v23, v121
	v_bcnt_u32_b32 v124, v22, v124
	s_nop 0
	v_cndmask_b32_e64 v23, 0, 1, s[60:61]
	v_cndmask_b32_e32 v23, v126, v23, vcc
	v_and_b32_e32 v23, 1, v23
	v_cmp_eq_u32_e32 vcc, 1, v23
	s_andn2_b64 s[60:61], s[62:63], exec
	s_and_b64 s[62:63], vcc, exec
	s_or_b64 s[62:63], s[60:61], s[62:63]
.LBB0_622:
	s_and_b64 s[60:61], s[64:65], s[2:3]
	s_mov_b64 vcc, s[60:61]
	s_nop 0
	s_cbranch_vccz .LBB0_626
	s_nop 0
	v_lshrrev_b64 v[22:23], v114, vcc
	v_and_b32_e32 v23, v22, v109
	v_bcnt_u32_b32 v23, v23, v115
	v_cmp_gt_i32_e32 vcc, s85, v23
	s_and_b64 s[64:65], s[60:61], vcc
	s_and_saveexec_b64 s[60:61], s[64:65]
	v_lshl_add_u32 v23, v23, 3, v111
	ds_write_b64 v23, v[20:21]
	s_or_b64 exec, exec, s[60:61]
	v_bcnt_u32_b32 v115, v22, v115
.LBB0_626:
	v_med3_f32 v20, v24, 0, v187
	v_mul_f32_e32 v20, v56, v20
	v_med3_f32 v22, v25, 0, v187
	v_fmac_f32_e32 v20, v57, v22
	v_med3_f32 v22, v26, 0, v187
	v_fmac_f32_e32 v20, v58, v22
	v_med3_f32 v22, v27, 0, v187
	v_fmac_f32_e32 v20, v59, v22
	s_mov_b64 s[60:61], s[62:63]
	s_nop 0
	v_not_b32_e32 v22, v20
	v_or_b32_e32 v23, 0x80000000, v20
	v_cmp_gt_i32_e32 vcc, 0, v20
	s_nop 1
	v_cndmask_b32_e32 v20, v23, v22, vcc
	v_cmp_ge_u32_e32 vcc, v20, v71
	s_and_b64 s[64:65], s[66:67], vcc
	v_cmp_ge_u32_e32 vcc, v20, v70
	s_and_b64 s[70:71], s[66:67], vcc
	v_cmp_lt_u32_e64 s[62:63], v20, v71
	s_and_b64 vcc, exec, s[58:59]
	s_and_b64 s[70:71], s[70:71], s[62:63]
	s_cbranch_vccnz .LBB0_628
	s_and_b64 vcc, s[70:71], s[8:9]
	s_mov_b64 s[62:63], vcc
	s_nop 0
	v_cndmask_b32_e64 v24, 0, 1, s[64:65]
	s_nop 0
	v_lshrrev_b64 v[22:23], v114, s[62:63]
	v_and_b32_e32 v23, v22, v109
	v_bcnt_u32_b32 v23, v23, v122
	v_cmp_lt_i32_e64 s[62:63], v23, v123
	v_bcnt_u32_b32 v122, v22, v122
	s_nop 0
	v_cndmask_b32_e64 v23, 0, 1, s[62:63]
	v_cndmask_b32_e32 v23, v24, v23, vcc
	v_and_b32_e32 v23, 1, v23
	v_cmp_eq_u32_e32 vcc, 1, v23
	s_andn2_b64 s[62:63], s[64:65], exec
	s_and_b64 s[64:65], vcc, exec
	s_or_b64 s[64:65], s[62:63], s[64:65]
.LBB0_628:
	s_and_b64 s[62:63], s[70:71], s[6:7]
	s_mov_b64 vcc, s[62:63]
	s_nop 0
	s_cbranch_vccz .LBB0_632
	s_nop 0
	v_lshrrev_b64 v[22:23], v114, vcc
	v_and_b32_e32 v23, v22, v109
	v_bcnt_u32_b32 v23, v23, v113
	v_cmp_gt_i32_e32 vcc, s85, v23
	s_and_b64 s[70:71], s[62:63], vcc
	s_and_saveexec_b64 s[62:63], s[70:71]
	v_lshl_add_u32 v23, v23, 3, v111
	ds_write_b64 v23, v[20:21] offset:1472
	s_or_b64 exec, exec, s[62:63]
	v_bcnt_u32_b32 v113, v22, v113
.LBB0_632:
	v_med3_f32 v20, v28, 0, v187
	v_mul_f32_e32 v20, v60, v20
	v_med3_f32 v22, v29, 0, v187
	v_fmac_f32_e32 v20, v61, v22
	v_med3_f32 v22, v30, 0, v187
	v_fmac_f32_e32 v20, v62, v22
	v_med3_f32 v22, v31, 0, v187
	v_fmac_f32_e32 v20, v63, v22
	s_mov_b64 s[62:63], s[64:65]
	s_nop 0
	v_not_b32_e32 v22, v20
	v_or_b32_e32 v23, 0x80000000, v20
	v_cmp_gt_i32_e32 vcc, 0, v20
	s_nop 1
	v_cndmask_b32_e32 v20, v23, v22, vcc
	v_cmp_ge_u32_e32 vcc, v20, v73
	s_and_b64 s[70:71], s[66:67], vcc
	v_cmp_ge_u32_e32 vcc, v20, v72
	s_and_b64 s[72:73], s[66:67], vcc
	v_cmp_lt_u32_e64 s[64:65], v20, v73
	s_and_b64 vcc, exec, s[58:59]
	s_and_b64 s[72:73], s[72:73], s[64:65]
	s_cbranch_vccnz .LBB0_634
	s_and_b64 vcc, s[72:73], s[12:13]
	s_mov_b64 s[64:65], vcc
	s_nop 0
	v_cndmask_b32_e64 v24, 0, 1, s[70:71]
	s_nop 0
	v_lshrrev_b64 v[22:23], v114, s[64:65]
	v_and_b32_e32 v23, v22, v109
	v_bcnt_u32_b32 v23, v23, v120
	v_cmp_lt_i32_e64 s[64:65], v23, v125
	v_bcnt_u32_b32 v120, v22, v120
	s_nop 0
	v_cndmask_b32_e64 v23, 0, 1, s[64:65]
	v_cndmask_b32_e32 v23, v24, v23, vcc
	v_and_b32_e32 v23, 1, v23
	v_cmp_eq_u32_e32 vcc, 1, v23
	s_andn2_b64 s[64:65], s[70:71], exec
	s_and_b64 s[70:71], vcc, exec
	s_or_b64 s[70:71], s[64:65], s[70:71]
.LBB0_634:
	s_and_b64 s[64:65], s[72:73], s[10:11]
	s_mov_b64 vcc, s[64:65]
	s_nop 0
	s_cbranch_vccz .LBB0_638
	s_nop 0
	v_lshrrev_b64 v[22:23], v114, vcc
	v_and_b32_e32 v23, v22, v109
	v_bcnt_u32_b32 v23, v23, v2
	v_cmp_gt_i32_e32 vcc, s85, v23
	s_and_b64 s[72:73], s[64:65], vcc
	s_and_saveexec_b64 s[64:65], s[72:73]
	v_lshl_add_u32 v23, v23, 3, v111
	ds_write_b64 v23, v[20:21] offset:2944
	s_or_b64 exec, exec, s[64:65]
	v_bcnt_u32_b32 v2, v22, v2
; DI void attn_item(const Params& P, unsigned char* smem, bool samp, int b, int c) {
;     ...
;         for (int hf = 0; hf < 2; ++hf) {
;           const bool valid = !tail || ((kt * 64 + hf * 32 + l32) < nkeys);
;           for (int i = 0; i < 4; ++i) {
;             const unsigned key = mono_key(sc[i][hf]);
;             bool sel = valid && (key >= khi[i]);
;             const bool inb = valid && (key >= klo[i]) && (key < khi[i]);
;             const bool zb = (bst[i] == 255);
;             if (anyzb) {
;               const unsigned long long bal = __ballot(inb && zb);
;               const unsigned mym = g ? (unsigned)(bal >> 32) : (unsigned)bal;
;               const int rank = __popc(mym & ltmask);
;               sel = sel || (inb && zb && (seen[i] + rank < nd[i]));
;               seen[i] += __popc(mym);
;             }
;             const bool cand = inb && !zb;
;             const unsigned long long cb = __ballot(cand);
;             if (cb != 0ull) {
;               const unsigned mym = g ? (unsigned)(cb >> 32) : (unsigned)cb;
;               const int slot = cbase[i] + __popc(mym & ltmask);
;               if (cand && slot < CAND_CAP)
;                 lst[(g + 2 * i) * CAND_CAP + slot] = make_uint2(key, (unsigned)(kt * 64 + hf * 32 + l32));
;               cbase[i] += __popc(mym);
;             }
;             const unsigned long long sb = __ballot(sel);
;             mv = (lane == (2 * i) * 2 + hf) ? (unsigned)sb : mv;
;             mv = (lane == (2 * i + 1) * 2 + hf) ? (unsigned)(sb >> 32) : mv;
;           }
.LBB0_638:
	v_med3_f32 v20, v32, 0, v187
	v_mul_f32_e32 v20, v64, v20
	v_med3_f32 v22, v33, 0, v187
	v_fmac_f32_e32 v20, v65, v22
	v_med3_f32 v22, v34, 0, v187
	v_fmac_f32_e32 v20, v66, v22
	v_med3_f32 v22, v35, 0, v187
	v_fmac_f32_e32 v20, v67, v22
	s_mov_b64 s[64:65], s[70:71]
	s_nop 0
	v_not_b32_e32 v22, v20
	v_or_b32_e32 v23, 0x80000000, v20
	v_cmp_gt_i32_e32 vcc, 0, v20
	s_nop 1
	v_cndmask_b32_e32 v20, v23, v22, vcc
	v_cmp_ge_u32_e32 vcc, v20, v75
	s_and_b64 s[70:71], s[66:67], vcc
	v_cmp_ge_u32_e32 vcc, v20, v74
	s_and_b64 s[72:73], s[66:67], vcc
	v_cmp_lt_u32_e64 s[66:67], v20, v75
	s_and_b64 vcc, exec, s[58:59]
	s_and_b64 s[72:73], s[72:73], s[66:67]
	s_cbranch_vccnz .LBB0_640
	s_and_b64 vcc, s[72:73], s[16:17]
	s_mov_b64 s[66:67], vcc
	s_nop 0
	v_cndmask_b32_e64 v24, 0, 1, s[70:71]
	s_nop 0
	v_lshrrev_b64 v[22:23], v114, s[66:67]
	v_and_b32_e32 v23, v22, v109
	v_bcnt_u32_b32 v23, v23, v119
	v_cmp_lt_i32_e64 s[66:67], v23, v127
	v_bcnt_u32_b32 v119, v22, v119
	s_nop 0
	v_cndmask_b32_e64 v23, 0, 1, s[66:67]
	v_cndmask_b32_e32 v23, v24, v23, vcc
	v_and_b32_e32 v23, 1, v23
	v_cmp_eq_u32_e32 vcc, 1, v23
	s_andn2_b64 s[66:67], s[70:71], exec
	s_and_b64 s[70:71], vcc, exec
	s_or_b64 s[70:71], s[66:67], s[70:71]
.LBB0_640:
	s_and_b64 s[66:67], s[72:73], s[14:15]
	s_mov_b64 vcc, s[66:67]
	s_nop 0
	s_cbranch_vccz .LBB0_644
	s_nop 0
	v_lshrrev_b64 v[22:23], v114, vcc
	v_and_b32_e32 v23, v22, v109
	v_bcnt_u32_b32 v23, v23, v1
	v_cmp_gt_i32_e32 vcc, s85, v23
	s_and_b64 s[72:73], s[66:67], vcc
	s_and_saveexec_b64 s[66:67], s[72:73]
	v_lshl_add_u32 v23, v23, 3, v111
	ds_write_b64 v23, v[20:21] offset:4416
	s_or_b64 exec, exec, s[66:67]
	v_bcnt_u32_b32 v1, v22, v1
.LBB0_644:
	v_med3_f32 v4, v4, 0, v187
	v_mul_f32_e32 v4, v52, v4
	v_med3_f32 v5, v5, 0, v187
	v_fmac_f32_e32 v4, v53, v5
	v_med3_f32 v5, v6, 0, v187
	v_fmac_f32_e32 v4, v54, v5
	v_med3_f32 v5, v7, 0, v187
	v_fmac_f32_e32 v4, v55, v5
	s_mov_b64 s[66:67], s[70:71]
	s_nop 0
	v_add_u32_e32 v5, 32, v21
	v_cmp_gt_u32_e32 vcc, s0, v5
	s_or_b64 s[74:75], s[68:69], vcc
	v_not_b32_e32 v6, v4
	v_or_b32_e32 v7, 0x80000000, v4
	v_cmp_gt_i32_e32 vcc, 0, v4
	s_nop 1
	v_cndmask_b32_e32 v4, v7, v6, vcc
	v_cmp_ge_u32_e32 vcc, v4, v69
	s_and_b64 s[70:71], s[74:75], vcc
	v_cmp_ge_u32_e32 vcc, v4, v68
	s_and_b64 s[72:73], s[74:75], vcc
	v_cmp_lt_u32_e64 s[68:69], v4, v69
	s_and_b64 vcc, exec, s[58:59]
	s_and_b64 s[72:73], s[72:73], s[68:69]
	s_cbranch_vccnz .LBB0_646
	s_and_b64 vcc, s[18:19], s[72:73]
	s_mov_b64 s[68:69], vcc
	s_nop 0
	v_cndmask_b32_e64 v20, 0, 1, s[70:71]
	s_nop 0
	v_lshrrev_b64 v[6:7], v114, s[68:69]
	v_and_b32_e32 v7, v6, v109
	v_bcnt_u32_b32 v7, v7, v124
	v_cmp_lt_i32_e64 s[68:69], v7, v121
	v_bcnt_u32_b32 v124, v6, v124
	s_nop 0
	v_cndmask_b32_e64 v7, 0, 1, s[68:69]
	v_cndmask_b32_e32 v7, v20, v7, vcc
	v_and_b32_e32 v7, 1, v7
	v_cmp_eq_u32_e32 vcc, 1, v7
	s_andn2_b64 s[68:69], s[70:71], exec
	s_and_b64 s[70:71], vcc, exec
	s_or_b64 s[70:71], s[68:69], s[70:71]
.LBB0_646:
	s_and_b64 s[68:69], s[72:73], s[2:3]
	s_mov_b64 vcc, s[68:69]
	s_nop 0
	s_cbranch_vccz .LBB0_650
	s_nop 0
	v_lshrrev_b64 v[6:7], v114, vcc
	v_and_b32_e32 v7, v6, v109
	v_bcnt_u32_b32 v7, v7, v115
	v_cmp_gt_i32_e32 vcc, s85, v7
	s_and_b64 s[72:73], s[68:69], vcc
	s_and_saveexec_b64 s[68:69], s[72:73]
	v_lshl_add_u32 v7, v7, 3, v111
	ds_write_b64 v7, v[4:5]
	s_or_b64 exec, exec, s[68:69]
	v_bcnt_u32_b32 v115, v6, v115
.LBB0_650:
	v_med3_f32 v4, v8, 0, v187
	v_mul_f32_e32 v4, v56, v4
	v_med3_f32 v6, v9, 0, v187
	v_fmac_f32_e32 v4, v57, v6
	v_med3_f32 v6, v10, 0, v187
	v_fmac_f32_e32 v4, v58, v6
	v_med3_f32 v6, v11, 0, v187
	v_fmac_f32_e32 v4, v59, v6
	s_mov_b64 s[68:69], s[70:71]
	s_nop 0
	v_not_b32_e32 v6, v4
	v_or_b32_e32 v7, 0x80000000, v4
	v_cmp_gt_i32_e32 vcc, 0, v4
	s_nop 1
	v_cndmask_b32_e32 v4, v7, v6, vcc
	v_cmp_ge_u32_e32 vcc, v4, v71
	s_and_b64 s[72:73], s[74:75], vcc
	v_cmp_ge_u32_e32 vcc, v4, v70
	s_and_b64 s[76:77], s[74:75], vcc
	v_cmp_lt_u32_e64 s[70:71], v4, v71
	s_and_b64 vcc, exec, s[58:59]
	s_and_b64 s[78:79], s[76:77], s[70:71]
	s_cbranch_vccnz .LBB0_652
	s_and_b64 vcc, s[78:79], s[8:9]
	s_mov_b64 s[70:71], vcc
	s_nop 0
	v_cndmask_b32_e64 v8, 0, 1, s[72:73]
	s_nop 0
	v_lshrrev_b64 v[6:7], v114, s[70:71]
	v_and_b32_e32 v7, v6, v109
	v_bcnt_u32_b32 v7, v7, v122
	v_cmp_lt_i32_e64 s[70:71], v7, v123
	v_bcnt_u32_b32 v122, v6, v122
	s_nop 0
	v_cndmask_b32_e64 v7, 0, 1, s[70:71]
	v_cndmask_b32_e32 v7, v8, v7, vcc
	v_and_b32_e32 v7, 1, v7
	v_cmp_eq_u32_e32 vcc, 1, v7
	s_andn2_b64 s[70:71], s[72:73], exec
	s_and_b64 s[72:73], vcc, exec
	s_or_b64 s[72:73], s[70:71], s[72:73]
; DI void attn_item(const Params& P, unsigned char* smem, bool samp, int b, int c) {
;     ...
;         for (int hf = 0; hf < 2; ++hf) {
;           const bool valid = !tail || ((kt * 64 + hf * 32 + l32) < nkeys);
;           for (int i = 0; i < 4; ++i) {
;             const unsigned key = mono_key(sc[i][hf]);
;             bool sel = valid && (key >= khi[i]);
;             const bool inb = valid && (key >= klo[i]) && (key < khi[i]);
;             const bool zb = (bst[i] == 255);
;             if (anyzb) {
;               const unsigned long long bal = __ballot(inb && zb);
;               const unsigned mym = g ? (unsigned)(bal >> 32) : (unsigned)bal;
;               const int rank = __popc(mym & ltmask);
;               sel = sel || (inb && zb && (seen[i] + rank < nd[i]));
;               seen[i] += __popc(mym);
;             }
;             const bool cand = inb && !zb;
;             const unsigned long long cb = __ballot(cand);
;             if (cb != 0ull) {
;               const unsigned mym = g ? (unsigned)(cb >> 32) : (unsigned)cb;
;               const int slot = cbase[i] + __popc(mym & ltmask);
;               if (cand && slot < CAND_CAP)
;                 lst[(g + 2 * i) * CAND_CAP + slot] = make_uint2(key, (unsigned)(kt * 64 + hf * 32 + l32));
;               cbase[i] += __popc(mym);
;             }
;             const unsigned long long sb = __ballot(sel);
;             mv = (lane == (2 * i) * 2 + hf) ? (unsigned)sb : mv;
;             mv = (lane == (2 * i + 1) * 2 + hf) ? (unsigned)(sb >> 32) : mv;
;           }
;         }
;         if (lane < 16) maskl[(kt * 64 + 8 * wid) * 2 + lane] = mv;
.LBB0_652:
	s_and_b64 s[70:71], s[78:79], s[6:7]
	s_mov_b64 vcc, s[70:71]
	s_nop 0
	s_cbranch_vccz .LBB0_656
	s_nop 0
	v_lshrrev_b64 v[6:7], v114, vcc
	v_and_b32_e32 v7, v6, v109
	v_bcnt_u32_b32 v7, v7, v113
	v_cmp_gt_i32_e32 vcc, s85, v7
	s_and_b64 s[76:77], s[70:71], vcc
	s_and_saveexec_b64 s[70:71], s[76:77]
	v_lshl_add_u32 v7, v7, 3, v111
	ds_write_b64 v7, v[4:5] offset:1472
	s_or_b64 exec, exec, s[70:71]
	v_bcnt_u32_b32 v113, v6, v113
.LBB0_656:
	v_med3_f32 v4, v12, 0, v187
	v_mul_f32_e32 v4, v60, v4
	v_med3_f32 v6, v13, 0, v187
	v_fmac_f32_e32 v4, v61, v6
	v_med3_f32 v6, v14, 0, v187
	v_fmac_f32_e32 v4, v62, v6
	v_med3_f32 v6, v15, 0, v187
	v_fmac_f32_e32 v4, v63, v6
	s_mov_b64 s[70:71], s[72:73]
	s_nop 0
	v_not_b32_e32 v6, v4
	v_or_b32_e32 v7, 0x80000000, v4
	v_cmp_gt_i32_e32 vcc, 0, v4
	s_nop 1
	v_cndmask_b32_e32 v4, v7, v6, vcc
	v_cmp_ge_u32_e32 vcc, v4, v73
	s_and_b64 s[78:79], s[74:75], vcc
	v_cmp_ge_u32_e32 vcc, v4, v72
	s_and_b64 s[76:77], s[74:75], vcc
	v_cmp_lt_u32_e64 s[72:73], v4, v73
	s_and_b64 vcc, exec, s[58:59]
	s_and_b64 s[76:77], s[76:77], s[72:73]
	s_cbranch_vccnz .LBB0_658
	s_and_b64 vcc, s[76:77], s[12:13]
	s_mov_b64 s[72:73], vcc
	s_nop 0
	v_cndmask_b32_e64 v8, 0, 1, s[78:79]
	s_nop 0
	v_lshrrev_b64 v[6:7], v114, s[72:73]
	v_and_b32_e32 v7, v6, v109
	v_bcnt_u32_b32 v7, v7, v120
	v_cmp_lt_i32_e64 s[72:73], v7, v125
	v_bcnt_u32_b32 v120, v6, v120
	s_nop 0
	v_cndmask_b32_e64 v7, 0, 1, s[72:73]
	v_cndmask_b32_e32 v7, v8, v7, vcc
	v_and_b32_e32 v7, 1, v7
	v_cmp_eq_u32_e32 vcc, 1, v7
	s_andn2_b64 s[72:73], s[78:79], exec
	s_and_b64 s[78:79], vcc, exec
	s_or_b64 s[78:79], s[72:73], s[78:79]
.LBB0_658:
	s_and_b64 s[72:73], s[76:77], s[10:11]
	s_mov_b64 vcc, s[72:73]
	s_nop 0
	s_cbranch_vccz .LBB0_662
	s_nop 0
	v_lshrrev_b64 v[6:7], v114, vcc
	v_and_b32_e32 v7, v6, v109
	v_bcnt_u32_b32 v7, v7, v2
	v_cmp_gt_i32_e32 vcc, s85, v7
	s_and_b64 s[76:77], s[72:73], vcc
	s_and_saveexec_b64 s[72:73], s[76:77]
	v_lshl_add_u32 v7, v7, 3, v111
	ds_write_b64 v7, v[4:5] offset:2944
	s_or_b64 exec, exec, s[72:73]
	v_bcnt_u32_b32 v2, v6, v2
.LBB0_662:
	v_med3_f32 v4, v16, 0, v187
	v_mul_f32_e32 v4, v64, v4
	v_med3_f32 v6, v17, 0, v187
	v_fmac_f32_e32 v4, v65, v6
	v_med3_f32 v6, v18, 0, v187
	v_fmac_f32_e32 v4, v66, v6
	v_med3_f32 v6, v19, 0, v187
	v_fmac_f32_e32 v4, v67, v6
	s_mov_b64 s[72:73], s[78:79]
	s_nop 0
	v_not_b32_e32 v6, v4
	v_or_b32_e32 v7, 0x80000000, v4
	v_cmp_gt_i32_e32 vcc, 0, v4
	s_nop 1
	v_cndmask_b32_e32 v4, v7, v6, vcc
	v_cmp_ge_u32_e32 vcc, v4, v75
	s_and_b64 s[78:79], s[74:75], vcc
	v_cmp_ge_u32_e32 vcc, v4, v74
	s_and_b64 s[76:77], s[74:75], vcc
	v_cmp_lt_u32_e64 s[74:75], v4, v75
	s_and_b64 vcc, exec, s[58:59]
	s_and_b64 s[74:75], s[76:77], s[74:75]
	s_cbranch_vccnz .LBB0_664
	s_and_b64 vcc, s[74:75], s[16:17]
	s_mov_b64 s[58:59], vcc
	s_nop 0
	v_cndmask_b32_e64 v8, 0, 1, s[78:79]
	s_nop 0
	v_lshrrev_b64 v[6:7], v114, s[58:59]
	v_and_b32_e32 v7, v6, v109
	v_bcnt_u32_b32 v7, v7, v119
	v_cmp_lt_i32_e64 s[58:59], v7, v127
	v_bcnt_u32_b32 v119, v6, v119
	s_nop 0
	v_cndmask_b32_e64 v7, 0, 1, s[58:59]
	v_cndmask_b32_e32 v7, v8, v7, vcc
	v_and_b32_e32 v7, 1, v7
	v_cmp_eq_u32_e32 vcc, 1, v7
	s_andn2_b64 s[58:59], s[78:79], exec
	s_and_b64 s[76:77], vcc, exec
	s_or_b64 s[78:79], s[58:59], s[76:77]
.LBB0_664:
	s_and_b64 s[58:59], s[74:75], s[14:15]
	s_mov_b64 vcc, s[58:59]
	s_nop 0
	s_cbranch_vccz .LBB0_668
	s_nop 0
	v_lshrrev_b64 v[6:7], v114, vcc
	v_and_b32_e32 v7, v6, v109
	v_bcnt_u32_b32 v7, v7, v1
	v_cmp_gt_i32_e32 vcc, s85, v7
	s_and_b64 s[74:75], s[58:59], vcc
	s_and_saveexec_b64 s[58:59], s[74:75]
	v_lshl_add_u32 v7, v7, 3, v111
	ds_write_b64 v7, v[4:5] offset:4416
	s_or_b64 exec, exec, s[58:59]
	v_bcnt_u32_b32 v1, v6, v1
.LBB0_668:
	s_mov_b64 vcc, s[78:79]
	s_nop 0
	s_and_saveexec_b64 s[58:59], s[22:23]
	s_cbranch_execz .LBB0_617
	v_mov_b32_e32 v4, s60
	v_cndmask_b32_e64 v4, 0, v4, s[24:25]
	v_mov_b32_e32 v5, s61
	v_cndmask_b32_e64 v4, v4, v5, s[26:27]
	v_mov_b32_e32 v5, s62
	v_cndmask_b32_e64 v4, v4, v5, s[28:29]
	v_mov_b32_e32 v5, s63
	v_cndmask_b32_e64 v4, v4, v5, s[30:31]
	v_mov_b32_e32 v5, s64
	v_cndmask_b32_e64 v4, v4, v5, s[34:35]
	v_mov_b32_e32 v5, s65
	v_cndmask_b32_e64 v4, v4, v5, s[36:37]
	v_mov_b32_e32 v5, s66
	v_cndmask_b32_e64 v4, v4, v5, s[38:39]
	v_mov_b32_e32 v5, s67
	v_cndmask_b32_e64 v4, v4, v5, s[40:41]
	v_mov_b32_e32 v5, s68
	v_cndmask_b32_e64 v4, v4, v5, s[42:43]
	v_mov_b32_e32 v5, s69
	v_cndmask_b32_e64 v4, v4, v5, s[44:45]
	v_mov_b32_e32 v5, s70
	v_cndmask_b32_e64 v4, v4, v5, s[46:47]
	v_mov_b32_e32 v5, s71
	v_cndmask_b32_e64 v4, v4, v5, s[48:49]
	v_mov_b32_e32 v5, s72
	v_cndmask_b32_e64 v4, v4, v5, s[50:51]
	v_mov_b32_e32 v5, s73
	v_cndmask_b32_e64 v4, v4, v5, s[52:53]
	v_mov_b32_e32 v5, vcc_lo
	v_cndmask_b32_e64 v4, v4, v5, s[56:57]
	v_mov_b32_e32 v5, vcc_hi
	v_cndmask_b32_e64 v4, v4, v5, s[54:55]
	ds_write_b32 v118, v4
	s_branch .LBB0_617
